# MoBA K tile staged by LDS-DMA with swizzled source addresses, K ds_writes removed
# baseline (speedup 1.0000x reference)
.LBB0_894:
	v_sub_co_u32_e64 v116, s[38:39], s7, 4
	s_xor_b64 s[4:5], s[38:39], -1
	s_add_i32 s44, s9, s85
	s_cmp_gt_u32 s7, 2
	s_cselect_b64 s[36:37], -1, 0
	s_add_i32 s45, s44, 64
	s_add_i32 s46, s85, 0xffffff40
	s_cmp_lt_u32 s7, 3
	s_cselect_b64 s[62:63], -1, 0
	s_and_b64 s[42:43], s[62:63], exec
	s_cselect_b32 s45, s45, s46
	v_lshrrev_b32_e32 v114, 4, v170
	v_and_b32_e32 v115, 15, v170
	v_and_b32_e32 v100, 15, v114
	v_xor_b32_e32 v100, v115, v100
	v_mul_u32_u24_e32 v114, 0x3000, v114
	v_lshl_or_b32 v100, v100, 4, v114
	v_lshl_or_b32 v114, v115, 4, v114
	s_mul_i32 s42, s45, 0x3000
	s_add_i32 s43, s42, 0x60000
	v_add_u32_e32 v112, s42, v114
	v_add_u32_e32 v113, s43, v114
	v_add_u32_e32 v101, s43, v100
	v_add_u32_e32 v100, s42, v100
	s_and_b32 s86, s7, 1
	s_cselect_b32 m0, 0, 0x4400
	v_readlane_b32 s43, v254, 60
	s_lshl_b32 s43, s43, 10
	s_add_i32 m0, m0, s43
	v_ashrrev_i32_e32 v8, 2, v116
	global_load_lds_dwordx4 v100, s[24:25]
	s_add_i32 m0, m0, 0x2000
	s_mov_b64 s[40:41], -1
	global_load_lds_dwordx4 v101, s[24:25]
	global_load_dwordx4 v[104:107], v112, s[26:27]
	global_load_dwordx4 v[112:115], v113, s[26:27]
	v_lshlrev_b32_e64 v8, v8, 1
	s_and_b64 vcc, exec, s[4:5]
	s_cbranch_vccz .LBB0_897
	v_and_b32_e32 v116, v8, v193
	v_cmp_ne_u32_e32 vcc, 0, v116
	s_cmp_lg_u64 vcc, 0
	s_cselect_b64 s[42:43], -1, 0
	s_cbranch_execz .LBB0_898

.LBB0_912:
	s_lshl_b32 s4, s86, 6
	s_xor_b32 s38, s4, 64
	v_lshrrev_b32_e32 v120, 4, v170
	v_and_b32_e32 v119, 15, v170
	s_mul_i32 s4, s38, 0x120
	v_mul_u32_u24_e32 v116, 0x120, v120
	v_lshl_add_u32 v116, v119, 4, v116
	v_add_u32_e32 v116, s4, v116
	s_add_i32 s40, s7, 1
	s_add_i32 s85, s85, 64
	s_cmp_eq_u32 s7, s6
	s_waitcnt vmcnt(1)
	ds_write_b128 v116, v[104:107] offset:34816
	s_waitcnt vmcnt(0)
	ds_write_b128 v116, v[112:115] offset:44032
	s_waitcnt lgkmcnt(0)
	s_barrier
	s_cbranch_scc1 .LBB0_914
	s_mov_b32 s7, s40
	s_branch .LBB0_894
